# GEMM loop global loads in saddr form (SGPR row bases + one 32-bit lane offset per half) instead of 7 64-bit VALU address adds
# speedup vs baseline: 1.0071x; 1.0071x over previous
.LBB0_122:
	v_mov_b32_e32 v36, 0
	v_mov_b32_e32 v37, 0
	v_mov_b32_e32 v38, 0
	v_mov_b32_e32 v39, 0
	v_mov_b32_e32 v40, 0
	v_mov_b32_e32 v41, 0
	v_mov_b32_e32 v42, 0
	v_mov_b32_e32 v43, 0
	v_mov_b32_e32 v128, 0
	v_mov_b32_e32 v129, 0
	v_mov_b32_e32 v130, 0
	v_mov_b32_e32 v131, 0
	v_mov_b32_e32 v194, 0
	v_mov_b32_e32 v195, 0
	v_mov_b32_e32 v196, 0
	v_mov_b32_e32 v197, 0
	v_mov_b32_e32 v198, 0
	v_mov_b32_e32 v199, 0
	v_mov_b32_e32 v200, 0
	v_mov_b32_e32 v201, 0
	s_nop 1
	v_readfirstlane_b32 s10, v100
	v_readfirstlane_b32 s11, v101
	v_readfirstlane_b32 s12, v104
	v_readfirstlane_b32 s13, v105
	v_readfirstlane_b32 s14, v106
	v_readfirstlane_b32 s15, v107
	v_readfirstlane_b32 s16, v108
	v_readfirstlane_b32 s17, v109
	v_readfirstlane_b32 s18, v102
	v_readfirstlane_b32 s19, v103
	v_readfirstlane_b32 s20, v110
	v_readfirstlane_b32 s21, v111
	v_readfirstlane_b32 s22, v112
	v_readfirstlane_b32 s23, v113
	v_subrev_u32_e32 v140, s10, v100
	v_subrev_u32_e32 v141, s18, v102
	s_nop 4
.Lrs1_top:
	s_add_i32 s7, s6, 64
	s_min_u32 s8, s7, 0xae0
	s_lshl_b32 s78, s8, 1
	ds_read_b128 v[52:55], v116 offset:0
	ds_read_b128 v[48:51], v116 offset:0x800
	ds_read_b128 v[44:47], v116 offset:0x1000
	ds_read_b128 v[96:99], v114 offset:0
	v_mfma_f32_32x32x16_bf16 a[144:159], v[128:131], v[40:43], a[144:159]
	ds_read_b128 v[92:95], v114 offset:0x800
	v_mfma_f32_32x32x16_bf16 a[160:175], v[128:131], v[36:39], a[160:175]
	ds_read_b128 v[88:91], v114 offset:0x1000
	v_add_u32_e32 v142, s78, v140
	v_add_u32_e32 v143, s78, v141
	global_load_dwordx4 v[64:67], v142, s[10:11]
	v_mfma_f32_32x32x16_bf16 a[176:191], v[128:131], v[194:197], a[176:191]
	ds_read_b128 v[56:59], v114 offset:0x1800
	global_load_dwordx4 v[60:63], v142, s[12:13]
	v_mfma_f32_32x32x16_bf16 a[32:47], v[198:201], v[40:43], a[32:47]
	global_load_dwordx4 v[72:75], v142, s[14:15]
	v_mfma_f32_32x32x16_bf16 a[16:31], v[198:201], v[36:39], a[16:31]
	global_load_dwordx4 v[68:71], v142, s[16:17]
	v_mfma_f32_32x32x16_bf16 a[0:15], v[198:201], v[194:197], a[0:15]
	global_load_dwordx4 v[84:87], v143, s[18:19]
	s_waitcnt lgkmcnt(3)
	v_mfma_f32_32x32x16_bf16 a[48:63], v[96:99], v[52:55], a[48:63]
	ds_read_b128 v[36:39], v117 offset:0
	v_mfma_f32_32x32x16_bf16 a[64:79], v[96:99], v[48:51], a[64:79]
	global_load_dwordx4 v[76:79], v143, s[20:21]
	v_mfma_f32_32x32x16_bf16 a[80:95], v[96:99], v[44:47], a[80:95]
	ds_read_b128 v[40:43], v117 offset:0x800
	s_waitcnt lgkmcnt(4)
	v_mfma_f32_32x32x16_bf16 a[96:111], v[92:95], v[52:55], a[96:111]
	global_load_dwordx4 v[80:83], v143, s[22:23]
	v_mfma_f32_32x32x16_bf16 a[112:127], v[92:95], v[48:51], a[112:127]
	ds_read_b128 v[120:123], v117 offset:0x1000
	v_mfma_f32_32x32x16_bf16 a[128:143], v[92:95], v[44:47], a[128:143]
	ds_read_b128 v[124:127], v115 offset:0
	s_waitcnt lgkmcnt(5)
	v_mfma_f32_32x32x16_bf16 a[144:159], v[88:91], v[52:55], a[144:159]
	ds_read_b128 v[128:131], v115 offset:0x800
	s_min_u32 s6, s6, 0xa80
	s_lshl_b32 s78, s6, 1
	v_mfma_f32_32x32x16_bf16 a[160:175], v[88:91], v[48:51], a[160:175]
	ds_read_b128 v[132:135], v115 offset:0x1000
	s_add_i32 s8, s78, 0xc0
	s_mov_b32 s9, s79
	v_mfma_f32_32x32x16_bf16 a[176:191], v[88:91], v[44:47], a[176:191]
	ds_read_b128 v[136:139], v115 offset:0x1800
	s_add_i32 s5, s5, 2
	s_cmpk_lt_u32 s5, 0x54
	s_waitcnt lgkmcnt(7)
	v_mfma_f32_32x32x16_bf16 a[32:47], v[56:59], v[52:55], a[32:47]
	s_waitcnt vmcnt(13)
	ds_write_b128 v118, v[4:7] offset:0x8000
	v_mfma_f32_32x32x16_bf16 a[16:31], v[56:59], v[48:51], a[16:31]
	s_waitcnt vmcnt(12)
	ds_write_b128 v118, v[8:11] offset:0x9000
	v_mfma_f32_32x32x16_bf16 a[0:15], v[56:59], v[44:47], a[0:15]
	s_waitcnt vmcnt(11)
	ds_write_b128 v118, v[12:15] offset:0xa000
	s_waitcnt lgkmcnt(6)
	v_mfma_f32_32x32x16_bf16 a[48:63], v[124:127], v[36:39], a[48:63]
	s_waitcnt vmcnt(10)
	ds_write_b128 v118, v[16:19] offset:0xb000
	v_mfma_f32_32x32x16_bf16 a[64:79], v[124:127], v[40:43], a[64:79]
	s_waitcnt vmcnt(9)
	ds_write_b128 v118, v[20:23] offset:0xc000
	v_mfma_f32_32x32x16_bf16 a[80:95], v[124:127], v[120:123], a[80:95]
	s_waitcnt vmcnt(8)
	ds_write_b128 v118, v[24:27] offset:0xd000
	s_waitcnt lgkmcnt(8)
	v_mfma_f32_32x32x16_bf16 a[96:111], v[128:131], v[36:39], a[96:111]
	s_waitcnt vmcnt(7)
	ds_write_b128 v118, v[28:31] offset:0xe000
	v_mfma_f32_32x32x16_bf16 a[112:127], v[128:131], v[40:43], a[112:127]
	v_mfma_f32_32x32x16_bf16 a[128:143], v[128:131], v[120:123], a[128:143]
	s_waitcnt lgkmcnt(0)
	s_barrier
	ds_read_b128 v[44:47], v116 offset:0x8000
	ds_read_b128 v[48:51], v116 offset:0x8800
	ds_read_b128 v[52:55], v116 offset:0x9000
	ds_read_b128 v[56:59], v114 offset:0x8000
	v_mfma_f32_32x32x16_bf16 a[144:159], v[132:135], v[36:39], a[144:159]
	ds_read_b128 v[88:91], v114 offset:0x8800
	v_mfma_f32_32x32x16_bf16 a[160:175], v[132:135], v[40:43], a[160:175]
	ds_read_b128 v[92:95], v114 offset:0x9000
	v_add_u32_e32 v142, s8, v140
	v_add_u32_e32 v143, s8, v141
	global_load_dwordx4 v[4:7], v142, s[10:11]
	v_mfma_f32_32x32x16_bf16 a[176:191], v[132:135], v[120:123], a[176:191]
	ds_read_b128 v[96:99], v114 offset:0x9800
	global_load_dwordx4 v[8:11], v142, s[12:13]
	v_mfma_f32_32x32x16_bf16 a[32:47], v[136:139], v[36:39], a[32:47]
	global_load_dwordx4 v[12:15], v142, s[14:15]
	v_mfma_f32_32x32x16_bf16 a[16:31], v[136:139], v[40:43], a[16:31]
	global_load_dwordx4 v[16:19], v142, s[16:17]
	v_mfma_f32_32x32x16_bf16 a[0:15], v[136:139], v[120:123], a[0:15]
	global_load_dwordx4 v[20:23], v143, s[18:19]
	s_waitcnt lgkmcnt(3)
	v_mfma_f32_32x32x16_bf16 a[48:63], v[56:59], v[44:47], a[48:63]
	ds_read_b128 v[40:43], v117 offset:0x8000
	v_mfma_f32_32x32x16_bf16 a[64:79], v[56:59], v[48:51], a[64:79]
	global_load_dwordx4 v[24:27], v143, s[20:21]
	v_mfma_f32_32x32x16_bf16 a[80:95], v[56:59], v[52:55], a[80:95]
	ds_read_b128 v[36:39], v117 offset:0x8800
	s_waitcnt lgkmcnt(4)
	v_mfma_f32_32x32x16_bf16 a[96:111], v[88:91], v[44:47], a[96:111]
	global_load_dwordx4 v[28:31], v143, s[22:23]
	v_mfma_f32_32x32x16_bf16 a[112:127], v[88:91], v[48:51], a[112:127]
	ds_read_b128 v[194:197], v117 offset:0x9000
	v_mfma_f32_32x32x16_bf16 a[128:143], v[88:91], v[52:55], a[128:143]
	ds_read_b128 v[120:123], v115 offset:0x8000
	s_waitcnt lgkmcnt(5)
	v_mfma_f32_32x32x16_bf16 a[144:159], v[92:95], v[44:47], a[144:159]
	ds_read_b128 v[124:127], v115 offset:0x8800
	v_mfma_f32_32x32x16_bf16 a[160:175], v[92:95], v[48:51], a[160:175]
	ds_read_b128 v[128:131], v115 offset:0x9000
	v_mfma_f32_32x32x16_bf16 a[176:191], v[92:95], v[52:55], a[176:191]
	ds_read_b128 v[198:201], v115 offset:0x9800
	s_waitcnt lgkmcnt(7)
	v_mfma_f32_32x32x16_bf16 a[32:47], v[96:99], v[44:47], a[32:47]
	s_waitcnt vmcnt(13)
	ds_write_b128 v118, v[64:67] offset:0
	v_mfma_f32_32x32x16_bf16 a[16:31], v[96:99], v[48:51], a[16:31]
	s_waitcnt vmcnt(12)
	ds_write_b128 v118, v[60:63] offset:0x1000
	v_mfma_f32_32x32x16_bf16 a[0:15], v[96:99], v[52:55], a[0:15]
	s_waitcnt vmcnt(11)
	ds_write_b128 v118, v[72:75] offset:0x2000
	s_waitcnt lgkmcnt(6)
	v_mfma_f32_32x32x16_bf16 a[48:63], v[120:123], v[40:43], a[48:63]
	s_waitcnt vmcnt(10)
	ds_write_b128 v118, v[68:71] offset:0x3000
	v_mfma_f32_32x32x16_bf16 a[64:79], v[120:123], v[36:39], a[64:79]
	s_waitcnt vmcnt(9)
	ds_write_b128 v118, v[84:87] offset:0x4000
	v_mfma_f32_32x32x16_bf16 a[80:95], v[120:123], v[194:197], a[80:95]
	s_waitcnt vmcnt(8)
	ds_write_b128 v118, v[76:79] offset:0x5000
	s_waitcnt lgkmcnt(8)
	v_mfma_f32_32x32x16_bf16 a[96:111], v[124:127], v[40:43], a[96:111]
	s_waitcnt vmcnt(7)
	ds_write_b128 v118, v[80:83] offset:0x6000
	v_mfma_f32_32x32x16_bf16 a[112:127], v[124:127], v[36:39], a[112:127]
	v_mfma_f32_32x32x16_bf16 a[128:143], v[124:127], v[194:197], a[128:143]
	s_waitcnt lgkmcnt(0)
	s_barrier
	s_cbranch_scc0 .Lrs1_last
	s_mov_b32 s6, s7
	s_branch .Lrs1_top
.Lrs1_last:
	s_mov_b32 s6, s7
	s_add_i32 s7, s6, 64
	s_min_u32 s8, s7, 0xae0
	s_lshl_b32 s78, s8, 1
	ds_read_b128 v[52:55], v116 offset:0
	ds_read_b128 v[48:51], v116 offset:0x800
	ds_read_b128 v[44:47], v116 offset:0x1000
	ds_read_b128 v[96:99], v114 offset:0
	v_mfma_f32_32x32x16_bf16 a[144:159], v[128:131], v[40:43], a[144:159]
	ds_read_b128 v[92:95], v114 offset:0x800
	v_mfma_f32_32x32x16_bf16 a[160:175], v[128:131], v[36:39], a[160:175]
	ds_read_b128 v[88:91], v114 offset:0x1000
	v_mfma_f32_32x32x16_bf16 a[176:191], v[128:131], v[194:197], a[176:191]
	ds_read_b128 v[56:59], v114 offset:0x1800
	v_mfma_f32_32x32x16_bf16 a[32:47], v[198:201], v[40:43], a[32:47]
	v_mfma_f32_32x32x16_bf16 a[16:31], v[198:201], v[36:39], a[16:31]
	v_mfma_f32_32x32x16_bf16 a[0:15], v[198:201], v[194:197], a[0:15]
	s_waitcnt lgkmcnt(3)
	v_mfma_f32_32x32x16_bf16 a[48:63], v[96:99], v[52:55], a[48:63]
	ds_read_b128 v[36:39], v117 offset:0
	v_mfma_f32_32x32x16_bf16 a[64:79], v[96:99], v[48:51], a[64:79]
	v_mfma_f32_32x32x16_bf16 a[80:95], v[96:99], v[44:47], a[80:95]
	ds_read_b128 v[40:43], v117 offset:0x800
	s_waitcnt lgkmcnt(4)
	v_mfma_f32_32x32x16_bf16 a[96:111], v[92:95], v[52:55], a[96:111]
	v_mfma_f32_32x32x16_bf16 a[112:127], v[92:95], v[48:51], a[112:127]
	ds_read_b128 v[120:123], v117 offset:0x1000
	v_mfma_f32_32x32x16_bf16 a[128:143], v[92:95], v[44:47], a[128:143]
	ds_read_b128 v[124:127], v115 offset:0
	s_waitcnt lgkmcnt(5)
	v_mfma_f32_32x32x16_bf16 a[144:159], v[88:91], v[52:55], a[144:159]
	ds_read_b128 v[128:131], v115 offset:0x800
	s_min_u32 s6, s6, 0xa80
	s_lshl_b32 s78, s6, 1
	v_mfma_f32_32x32x16_bf16 a[160:175], v[88:91], v[48:51], a[160:175]
	ds_read_b128 v[132:135], v115 offset:0x1000
	s_add_i32 s8, s78, 0xc0
	s_mov_b32 s9, s79
	v_mfma_f32_32x32x16_bf16 a[176:191], v[88:91], v[44:47], a[176:191]
	ds_read_b128 v[136:139], v115 offset:0x1800
	s_add_i32 s5, s5, 2
	s_cmpk_lt_u32 s5, 0x56
	s_waitcnt lgkmcnt(7)
	v_mfma_f32_32x32x16_bf16 a[32:47], v[56:59], v[52:55], a[32:47]
	s_waitcnt vmcnt(6)
	ds_write_b128 v118, v[4:7] offset:0x8000
	v_mfma_f32_32x32x16_bf16 a[16:31], v[56:59], v[48:51], a[16:31]
	s_waitcnt vmcnt(5)
	ds_write_b128 v118, v[8:11] offset:0x9000
	v_mfma_f32_32x32x16_bf16 a[0:15], v[56:59], v[44:47], a[0:15]
	s_waitcnt vmcnt(4)
	ds_write_b128 v118, v[12:15] offset:0xa000
	s_waitcnt lgkmcnt(6)
	v_mfma_f32_32x32x16_bf16 a[48:63], v[124:127], v[36:39], a[48:63]
	s_waitcnt vmcnt(3)
	ds_write_b128 v118, v[16:19] offset:0xb000
	v_mfma_f32_32x32x16_bf16 a[64:79], v[124:127], v[40:43], a[64:79]
	s_waitcnt vmcnt(2)
	ds_write_b128 v118, v[20:23] offset:0xc000
	v_mfma_f32_32x32x16_bf16 a[80:95], v[124:127], v[120:123], a[80:95]
	s_waitcnt vmcnt(1)
	ds_write_b128 v118, v[24:27] offset:0xd000
	s_waitcnt lgkmcnt(8)
	v_mfma_f32_32x32x16_bf16 a[96:111], v[128:131], v[36:39], a[96:111]
	s_waitcnt vmcnt(0)
	ds_write_b128 v118, v[28:31] offset:0xe000
	v_mfma_f32_32x32x16_bf16 a[112:127], v[128:131], v[40:43], a[112:127]
	v_mfma_f32_32x32x16_bf16 a[128:143], v[128:131], v[120:123], a[128:143]
	s_waitcnt lgkmcnt(0)
	s_barrier
	ds_read_b128 v[44:47], v116 offset:0x8000
	ds_read_b128 v[48:51], v116 offset:0x8800
	ds_read_b128 v[52:55], v116 offset:0x9000
	ds_read_b128 v[56:59], v114 offset:0x8000
	v_mfma_f32_32x32x16_bf16 a[144:159], v[132:135], v[36:39], a[144:159]
	ds_read_b128 v[88:91], v114 offset:0x8800
	v_mfma_f32_32x32x16_bf16 a[160:175], v[132:135], v[40:43], a[160:175]
	ds_read_b128 v[92:95], v114 offset:0x9000
	v_mfma_f32_32x32x16_bf16 a[176:191], v[132:135], v[120:123], a[176:191]
	ds_read_b128 v[96:99], v114 offset:0x9800
	v_mfma_f32_32x32x16_bf16 a[32:47], v[136:139], v[36:39], a[32:47]
	v_mfma_f32_32x32x16_bf16 a[16:31], v[136:139], v[40:43], a[16:31]
	v_mfma_f32_32x32x16_bf16 a[0:15], v[136:139], v[120:123], a[0:15]
	s_waitcnt lgkmcnt(3)
	v_mfma_f32_32x32x16_bf16 a[48:63], v[56:59], v[44:47], a[48:63]
	ds_read_b128 v[40:43], v117 offset:0x8000
	v_mfma_f32_32x32x16_bf16 a[64:79], v[56:59], v[48:51], a[64:79]
	v_mfma_f32_32x32x16_bf16 a[80:95], v[56:59], v[52:55], a[80:95]
	ds_read_b128 v[36:39], v117 offset:0x8800
	s_waitcnt lgkmcnt(4)
	v_mfma_f32_32x32x16_bf16 a[96:111], v[88:91], v[44:47], a[96:111]
	v_mfma_f32_32x32x16_bf16 a[112:127], v[88:91], v[48:51], a[112:127]
	ds_read_b128 v[194:197], v117 offset:0x9000
	v_mfma_f32_32x32x16_bf16 a[128:143], v[88:91], v[52:55], a[128:143]
	ds_read_b128 v[120:123], v115 offset:0x8000
	s_waitcnt lgkmcnt(5)
	v_mfma_f32_32x32x16_bf16 a[144:159], v[92:95], v[44:47], a[144:159]
	ds_read_b128 v[124:127], v115 offset:0x8800
	v_mfma_f32_32x32x16_bf16 a[160:175], v[92:95], v[48:51], a[160:175]
	ds_read_b128 v[128:131], v115 offset:0x9000
	v_mfma_f32_32x32x16_bf16 a[176:191], v[92:95], v[52:55], a[176:191]
	ds_read_b128 v[198:201], v115 offset:0x9800
	s_waitcnt lgkmcnt(7)
	v_mfma_f32_32x32x16_bf16 a[32:47], v[96:99], v[44:47], a[32:47]
	v_mfma_f32_32x32x16_bf16 a[16:31], v[96:99], v[48:51], a[16:31]
	v_mfma_f32_32x32x16_bf16 a[0:15], v[96:99], v[52:55], a[0:15]
	s_waitcnt lgkmcnt(3)
	v_mfma_f32_32x32x16_bf16 a[48:63], v[120:123], v[40:43], a[48:63]
	v_mfma_f32_32x32x16_bf16 a[64:79], v[120:123], v[36:39], a[64:79]
	v_mfma_f32_32x32x16_bf16 a[80:95], v[120:123], v[194:197], a[80:95]
	s_waitcnt lgkmcnt(2)
	v_mfma_f32_32x32x16_bf16 a[96:111], v[124:127], v[40:43], a[96:111]
	v_mfma_f32_32x32x16_bf16 a[112:127], v[124:127], v[36:39], a[112:127]
	v_mfma_f32_32x32x16_bf16 a[128:143], v[124:127], v[194:197], a[128:143]
	s_waitcnt lgkmcnt(0)
	s_barrier
	v_mfma_f32_32x32x16_bf16 a[144:159], v[128:131], v[40:43], a[144:159]
	v_mfma_f32_32x32x16_bf16 a[160:175], v[128:131], v[36:39], a[160:175]
	v_mfma_f32_32x32x16_bf16 a[176:191], v[128:131], v[194:197], a[176:191]
	s_nop 7
	s_nop 3
	s_branch .LBB0_120

.LBB0_141:
	v_mov_b32_e32 v40, 0
	v_mov_b32_e32 v41, 0
	v_mov_b32_e32 v42, 0
	v_mov_b32_e32 v43, 0
	v_mov_b32_e32 v94, 0
	v_mov_b32_e32 v95, 0
	v_mov_b32_e32 v96, 0
	v_mov_b32_e32 v97, 0
	v_mov_b32_e32 v128, 0
	v_mov_b32_e32 v129, 0
	v_mov_b32_e32 v130, 0
	v_mov_b32_e32 v131, 0
	v_mov_b32_e32 v132, 0
	v_mov_b32_e32 v133, 0
	v_mov_b32_e32 v134, 0
	v_mov_b32_e32 v135, 0
	s_nop 1
	v_readfirstlane_b32 s8, v68
	v_readfirstlane_b32 s9, v69
	v_readfirstlane_b32 s10, v72
	v_readfirstlane_b32 s11, v73
	v_readfirstlane_b32 s12, v74
	v_readfirstlane_b32 s13, v75
	v_readfirstlane_b32 s14, v76
	v_readfirstlane_b32 s15, v77
	v_readfirstlane_b32 s16, v70
	v_readfirstlane_b32 s17, v71
	v_readfirstlane_b32 s18, v78
	v_readfirstlane_b32 s19, v79
	v_subrev_u32_e32 v144, s8, v68
	v_subrev_u32_e32 v145, s16, v70
	s_nop 4
.Lrs2_top:
	s_add_i32 s5, s4, 64
	s_min_u32 s6, s5, 0xae0
	s_lshl_b32 s78, s6, 1
	ds_read_b128 v[48:51], v82 offset:0
	ds_read_b128 v[44:47], v82 offset:0x800
	ds_read_b128 v[64:67], v80 offset:0
	v_mfma_f32_32x32x16_bf16 a[96:111], v[94:97], v[40:43], a[96:111]
	ds_read_b128 v[60:63], v80 offset:0x800
	v_mfma_f32_32x32x16_bf16 a[112:127], v[94:97], v[128:131], a[112:127]
	ds_read_b128 v[56:59], v80 offset:0x1000
	v_add_u32_e32 v146, s78, v144
	v_add_u32_e32 v147, s78, v145
	global_load_dwordx4 v[106:109], v146, s[8:9]
	v_mfma_f32_32x32x16_bf16 a[16:31], v[132:135], v[40:43], a[16:31]
	ds_read_b128 v[52:55], v80 offset:0x1800
	global_load_dwordx4 v[110:113], v146, s[10:11]
	v_mfma_f32_32x32x16_bf16 a[0:15], v[132:135], v[128:131], a[0:15]
	global_load_dwordx4 v[114:117], v146, s[12:13]
	s_waitcnt lgkmcnt(3)
	v_mfma_f32_32x32x16_bf16 a[32:47], v[64:67], v[48:51], a[32:47]
	ds_read_b128 v[40:43], v83 offset:0
	v_mfma_f32_32x32x16_bf16 a[48:63], v[64:67], v[44:47], a[48:63]
	global_load_dwordx4 v[118:121], v146, s[14:15]
	s_waitcnt lgkmcnt(3)
	v_mfma_f32_32x32x16_bf16 a[64:79], v[60:63], v[48:51], a[64:79]
	ds_read_b128 v[86:89], v83 offset:0x800
	v_mfma_f32_32x32x16_bf16 a[80:95], v[60:63], v[44:47], a[80:95]
	global_load_dwordx4 v[122:125], v147, s[16:17]
	s_waitcnt lgkmcnt(3)
	v_mfma_f32_32x32x16_bf16 a[96:111], v[56:59], v[48:51], a[96:111]
	ds_read_b128 v[90:93], v81 offset:0
	v_mfma_f32_32x32x16_bf16 a[112:127], v[56:59], v[44:47], a[112:127]
	global_load_dwordx4 v[140:143], v147, s[18:19]
	s_waitcnt vmcnt(11)
	ds_write_b128 v84, v[4:7] offset:0x8000
	s_waitcnt lgkmcnt(4)
	v_mfma_f32_32x32x16_bf16 a[16:31], v[52:55], v[48:51], a[16:31]
	ds_read_b128 v[94:97], v81 offset:0x800
	s_min_u32 s4, s4, 0xa80
	s_lshl_b32 s78, s4, 1
	s_waitcnt vmcnt(10)
	ds_write_b128 v84, v[8:11] offset:0x9000
	v_mfma_f32_32x32x16_bf16 a[0:15], v[52:55], v[44:47], a[0:15]
	ds_read_b128 v[98:101], v81 offset:0x1000
	s_add_i32 s6, s78, 0xc0
	s_mov_b32 s7, s79
	s_waitcnt vmcnt(9)
	ds_write_b128 v84, v[12:15] offset:0xa000
	s_waitcnt lgkmcnt(5)
	v_mfma_f32_32x32x16_bf16 a[32:47], v[90:93], v[40:43], a[32:47]
	ds_read_b128 v[102:105], v81 offset:0x1800
	s_add_i32 s3, s3, 2
	s_cmpk_lt_u32 s3, 0x54
	s_waitcnt vmcnt(8)
	ds_write_b128 v84, v[16:19] offset:0xb000
	v_mfma_f32_32x32x16_bf16 a[48:63], v[90:93], v[86:89], a[48:63]
	s_waitcnt vmcnt(7)
	ds_write_b128 v84, v[20:23] offset:0xc000
	s_waitcnt lgkmcnt(6)
	v_mfma_f32_32x32x16_bf16 a[64:79], v[94:97], v[40:43], a[64:79]
	s_waitcnt vmcnt(6)
	ds_write_b128 v84, v[24:27] offset:0xd000
	v_mfma_f32_32x32x16_bf16 a[80:95], v[94:97], v[86:89], a[80:95]
	s_waitcnt lgkmcnt(0)
	s_barrier
	ds_read_b128 v[44:47], v82 offset:0x8000
	ds_read_b128 v[48:51], v82 offset:0x8800
	ds_read_b128 v[52:55], v80 offset:0x8000
	v_mfma_f32_32x32x16_bf16 a[96:111], v[98:101], v[40:43], a[96:111]
	ds_read_b128 v[56:59], v80 offset:0x8800
	v_mfma_f32_32x32x16_bf16 a[112:127], v[98:101], v[86:89], a[112:127]
	ds_read_b128 v[60:63], v80 offset:0x9000
	v_add_u32_e32 v146, s6, v144
	v_add_u32_e32 v147, s6, v145
	global_load_dwordx4 v[4:7], v146, s[8:9]
	v_mfma_f32_32x32x16_bf16 a[16:31], v[102:105], v[40:43], a[16:31]
	ds_read_b128 v[64:67], v80 offset:0x9800
	global_load_dwordx4 v[8:11], v146, s[10:11]
	v_mfma_f32_32x32x16_bf16 a[0:15], v[102:105], v[86:89], a[0:15]
	global_load_dwordx4 v[12:15], v146, s[12:13]
	s_waitcnt lgkmcnt(3)
	v_mfma_f32_32x32x16_bf16 a[32:47], v[52:55], v[44:47], a[32:47]
	ds_read_b128 v[40:43], v83 offset:0x8000
	v_mfma_f32_32x32x16_bf16 a[48:63], v[52:55], v[48:51], a[48:63]
	global_load_dwordx4 v[16:19], v146, s[14:15]
	s_waitcnt lgkmcnt(3)
	v_mfma_f32_32x32x16_bf16 a[64:79], v[56:59], v[44:47], a[64:79]
	ds_read_b128 v[128:131], v83 offset:0x8800
	v_mfma_f32_32x32x16_bf16 a[80:95], v[56:59], v[48:51], a[80:95]
	global_load_dwordx4 v[20:23], v147, s[16:17]
	s_waitcnt lgkmcnt(3)
	v_mfma_f32_32x32x16_bf16 a[96:111], v[60:63], v[44:47], a[96:111]
	ds_read_b128 v[86:89], v81 offset:0x8000
	v_mfma_f32_32x32x16_bf16 a[112:127], v[60:63], v[48:51], a[112:127]
	global_load_dwordx4 v[24:27], v147, s[18:19]
	s_waitcnt vmcnt(11)
	ds_write_b128 v84, v[106:109] offset:0
	s_waitcnt lgkmcnt(4)
	v_mfma_f32_32x32x16_bf16 a[16:31], v[64:67], v[44:47], a[16:31]
	ds_read_b128 v[90:93], v81 offset:0x8800
	s_waitcnt vmcnt(10)
	ds_write_b128 v84, v[110:113] offset:0x1000
	v_mfma_f32_32x32x16_bf16 a[0:15], v[64:67], v[48:51], a[0:15]
	ds_read_b128 v[94:97], v81 offset:0x9000
	s_waitcnt vmcnt(9)
	ds_write_b128 v84, v[114:117] offset:0x2000
	s_waitcnt lgkmcnt(5)
	v_mfma_f32_32x32x16_bf16 a[32:47], v[86:89], v[40:43], a[32:47]
	ds_read_b128 v[132:135], v81 offset:0x9800
	s_waitcnt vmcnt(8)
	ds_write_b128 v84, v[118:121] offset:0x3000
	v_mfma_f32_32x32x16_bf16 a[48:63], v[86:89], v[128:131], a[48:63]
	s_waitcnt vmcnt(7)
	ds_write_b128 v84, v[122:125] offset:0x4000
	s_waitcnt lgkmcnt(6)
	v_mfma_f32_32x32x16_bf16 a[64:79], v[90:93], v[40:43], a[64:79]
	s_waitcnt vmcnt(6)
	ds_write_b128 v84, v[140:143] offset:0x5000
	v_mfma_f32_32x32x16_bf16 a[80:95], v[90:93], v[128:131], a[80:95]
	s_waitcnt lgkmcnt(0)
	s_barrier
	s_cbranch_scc0 .Lrs2_last
	s_mov_b32 s4, s5
	s_branch .Lrs2_top

.LBB0_162:
	v_mov_b32_e32 v80, 0
	v_mov_b32_e32 v81, 0
	v_mov_b32_e32 v82, 0
	v_mov_b32_e32 v83, 0
	v_mov_b32_e32 v112, 0
	v_mov_b32_e32 v113, 0
	v_mov_b32_e32 v114, 0
	v_mov_b32_e32 v115, 0
	v_mov_b32_e32 v128, 0
	v_mov_b32_e32 v129, 0
	v_mov_b32_e32 v130, 0
	v_mov_b32_e32 v131, 0
	v_mov_b32_e32 v132, 0
	v_mov_b32_e32 v133, 0
	v_mov_b32_e32 v134, 0
	v_mov_b32_e32 v135, 0
	v_mov_b32_e32 v136, 0
	v_mov_b32_e32 v137, 0
	v_mov_b32_e32 v138, 0
	v_mov_b32_e32 v139, 0
	s_nop 1
	v_readfirstlane_b32 s8, v96
	v_readfirstlane_b32 s9, v97
	v_readfirstlane_b32 s10, v100
	v_readfirstlane_b32 s11, v101
	v_readfirstlane_b32 s12, v102
	v_readfirstlane_b32 s13, v103
	v_readfirstlane_b32 s14, v104
	v_readfirstlane_b32 s15, v105
	v_readfirstlane_b32 s16, v98
	v_readfirstlane_b32 s17, v99
	v_readfirstlane_b32 s18, v106
	v_readfirstlane_b32 s19, v107
	v_readfirstlane_b32 s20, v108
	v_readfirstlane_b32 s21, v109
	v_subrev_u32_e32 v140, s8, v96
	v_subrev_u32_e32 v141, s16, v98
	s_nop 4
.Lrs0_top:
	s_add_i32 s5, s4, 64
	s_min_u32 s6, s5, 0x3e0
	s_lshl_b32 s78, s6, 1
	ds_read_b128 v[44:47], v116 offset:0
	ds_read_b128 v[40:43], v116 offset:0x800
	ds_read_b128 v[36:39], v116 offset:0x1000
	ds_read_b128 v[92:95], v110 offset:0
	v_mfma_f32_32x32x16_bf16 a[144:159], v[136:139], v[80:83], a[144:159]
	ds_read_b128 v[88:91], v110 offset:0x800
	v_mfma_f32_32x32x16_bf16 a[160:175], v[136:139], v[112:115], a[160:175]
	ds_read_b128 v[84:87], v110 offset:0x1000
	v_add_u32_e32 v142, s78, v140
	v_add_u32_e32 v143, s78, v141
	global_load_dwordx4 v[56:59], v142, s[8:9]
	v_mfma_f32_32x32x16_bf16 a[176:191], v[136:139], v[128:131], a[176:191]
	ds_read_b128 v[48:51], v110 offset:0x1800
	global_load_dwordx4 v[52:55], v142, s[10:11]
	v_mfma_f32_32x32x16_bf16 a[32:47], v[132:135], v[80:83], a[32:47]
	global_load_dwordx4 v[64:67], v142, s[12:13]
	v_mfma_f32_32x32x16_bf16 a[16:31], v[132:135], v[112:115], a[16:31]
	global_load_dwordx4 v[60:63], v142, s[14:15]
	v_mfma_f32_32x32x16_bf16 a[0:15], v[132:135], v[128:131], a[0:15]
	global_load_dwordx4 v[76:79], v143, s[16:17]
	s_waitcnt lgkmcnt(3)
	v_mfma_f32_32x32x16_bf16 a[80:95], v[92:95], v[44:47], a[80:95]
	ds_read_b128 v[80:83], v117 offset:0
	v_mfma_f32_32x32x16_bf16 a[48:63], v[92:95], v[40:43], a[48:63]
	global_load_dwordx4 v[68:71], v143, s[18:19]
	v_mfma_f32_32x32x16_bf16 a[64:79], v[92:95], v[36:39], a[64:79]
	ds_read_b128 v[112:115], v117 offset:0x800
	s_waitcnt lgkmcnt(4)
	v_mfma_f32_32x32x16_bf16 a[96:111], v[88:91], v[44:47], a[96:111]
	global_load_dwordx4 v[72:75], v143, s[20:21]
	v_mfma_f32_32x32x16_bf16 a[112:127], v[88:91], v[40:43], a[112:127]
	ds_read_b128 v[120:123], v117 offset:0x1000
	v_mfma_f32_32x32x16_bf16 a[128:143], v[88:91], v[36:39], a[128:143]
	ds_read_b128 v[124:127], v111 offset:0
	s_waitcnt lgkmcnt(5)
	v_mfma_f32_32x32x16_bf16 a[144:159], v[84:87], v[44:47], a[144:159]
	ds_read_b128 v[128:131], v111 offset:0x800
	s_min_u32 s4, s4, 0x380
	s_lshl_b32 s78, s4, 1
	v_mfma_f32_32x32x16_bf16 a[160:175], v[84:87], v[40:43], a[160:175]
	ds_read_b128 v[132:135], v111 offset:0x1000
	s_add_i32 s6, s78, 0xc0
	s_mov_b32 s7, s79
	v_mfma_f32_32x32x16_bf16 a[176:191], v[84:87], v[36:39], a[176:191]
	ds_read_b128 v[136:139], v111 offset:0x1800
	s_add_i32 s3, s3, 2
	s_cmp_lt_u32 s3, 28
	s_waitcnt lgkmcnt(7)
	v_mfma_f32_32x32x16_bf16 a[32:47], v[48:51], v[44:47], a[32:47]
	s_waitcnt vmcnt(13)
	ds_write_b128 v118, v[4:7] offset:0x8000
	v_mfma_f32_32x32x16_bf16 a[16:31], v[48:51], v[40:43], a[16:31]
	s_waitcnt vmcnt(12)
	ds_write_b128 v118, v[8:11] offset:0x9000
	v_mfma_f32_32x32x16_bf16 a[0:15], v[48:51], v[36:39], a[0:15]
	s_waitcnt vmcnt(11)
	ds_write_b128 v118, v[12:15] offset:0xa000
	s_waitcnt lgkmcnt(6)
	v_mfma_f32_32x32x16_bf16 a[80:95], v[124:127], v[80:83], a[80:95]
	s_waitcnt vmcnt(10)
	ds_write_b128 v118, v[16:19] offset:0xb000
	v_mfma_f32_32x32x16_bf16 a[48:63], v[124:127], v[112:115], a[48:63]
	s_waitcnt vmcnt(9)
	ds_write_b128 v118, v[20:23] offset:0xc000
	v_mfma_f32_32x32x16_bf16 a[64:79], v[124:127], v[120:123], a[64:79]
	s_waitcnt vmcnt(8)
	ds_write_b128 v118, v[24:27] offset:0xd000
	s_waitcnt lgkmcnt(8)
	v_mfma_f32_32x32x16_bf16 a[96:111], v[128:131], v[80:83], a[96:111]
	s_waitcnt vmcnt(7)
	ds_write_b128 v118, v[28:31] offset:0xe000
	v_mfma_f32_32x32x16_bf16 a[112:127], v[128:131], v[112:115], a[112:127]
	v_mfma_f32_32x32x16_bf16 a[128:143], v[128:131], v[120:123], a[128:143]
	s_waitcnt lgkmcnt(0)
	s_barrier
	ds_read_b128 v[36:39], v116 offset:0x8000
	ds_read_b128 v[40:43], v116 offset:0x8800
	ds_read_b128 v[44:47], v116 offset:0x9000
	ds_read_b128 v[48:51], v110 offset:0x8000
	v_mfma_f32_32x32x16_bf16 a[144:159], v[132:135], v[80:83], a[144:159]
	ds_read_b128 v[84:87], v110 offset:0x8800
	v_mfma_f32_32x32x16_bf16 a[160:175], v[132:135], v[112:115], a[160:175]
	ds_read_b128 v[88:91], v110 offset:0x9000
	v_add_u32_e32 v142, s6, v140
	v_add_u32_e32 v143, s6, v141
	global_load_dwordx4 v[4:7], v142, s[8:9]
	v_mfma_f32_32x32x16_bf16 a[176:191], v[132:135], v[120:123], a[176:191]
	ds_read_b128 v[92:95], v110 offset:0x9800
	global_load_dwordx4 v[8:11], v142, s[10:11]
	v_mfma_f32_32x32x16_bf16 a[32:47], v[136:139], v[80:83], a[32:47]
	global_load_dwordx4 v[12:15], v142, s[12:13]
	v_mfma_f32_32x32x16_bf16 a[16:31], v[136:139], v[112:115], a[16:31]
	global_load_dwordx4 v[16:19], v142, s[14:15]
	v_mfma_f32_32x32x16_bf16 a[0:15], v[136:139], v[120:123], a[0:15]
	global_load_dwordx4 v[20:23], v143, s[16:17]
	s_waitcnt lgkmcnt(3)
	v_mfma_f32_32x32x16_bf16 a[80:95], v[48:51], v[36:39], a[80:95]
	ds_read_b128 v[80:83], v117 offset:0x8000
	v_mfma_f32_32x32x16_bf16 a[48:63], v[48:51], v[40:43], a[48:63]
	global_load_dwordx4 v[24:27], v143, s[18:19]
	v_mfma_f32_32x32x16_bf16 a[64:79], v[48:51], v[44:47], a[64:79]
	ds_read_b128 v[112:115], v117 offset:0x8800
	s_waitcnt lgkmcnt(4)
	v_mfma_f32_32x32x16_bf16 a[96:111], v[84:87], v[36:39], a[96:111]
	global_load_dwordx4 v[28:31], v143, s[20:21]
	v_mfma_f32_32x32x16_bf16 a[112:127], v[84:87], v[40:43], a[112:127]
	ds_read_b128 v[128:131], v117 offset:0x9000
	v_mfma_f32_32x32x16_bf16 a[128:143], v[84:87], v[44:47], a[128:143]
	ds_read_b128 v[120:123], v111 offset:0x8000
	s_waitcnt lgkmcnt(5)
	v_mfma_f32_32x32x16_bf16 a[144:159], v[88:91], v[36:39], a[144:159]
	ds_read_b128 v[124:127], v111 offset:0x8800
	v_mfma_f32_32x32x16_bf16 a[160:175], v[88:91], v[40:43], a[160:175]
	ds_read_b128 v[136:139], v111 offset:0x9000
	v_mfma_f32_32x32x16_bf16 a[176:191], v[88:91], v[44:47], a[176:191]
	ds_read_b128 v[132:135], v111 offset:0x9800
	s_waitcnt lgkmcnt(7)
	v_mfma_f32_32x32x16_bf16 a[32:47], v[92:95], v[36:39], a[32:47]
	s_waitcnt vmcnt(13)
	ds_write_b128 v118, v[56:59] offset:0
	v_mfma_f32_32x32x16_bf16 a[16:31], v[92:95], v[40:43], a[16:31]
	s_waitcnt vmcnt(12)
	ds_write_b128 v118, v[52:55] offset:0x1000
	v_mfma_f32_32x32x16_bf16 a[0:15], v[92:95], v[44:47], a[0:15]
	s_waitcnt vmcnt(11)
	ds_write_b128 v118, v[64:67] offset:0x2000
	s_waitcnt lgkmcnt(6)
	v_mfma_f32_32x32x16_bf16 a[80:95], v[120:123], v[80:83], a[80:95]
	s_waitcnt vmcnt(10)
	ds_write_b128 v118, v[60:63] offset:0x3000
	v_mfma_f32_32x32x16_bf16 a[48:63], v[120:123], v[112:115], a[48:63]
	s_waitcnt vmcnt(9)
	ds_write_b128 v118, v[76:79] offset:0x4000
	v_mfma_f32_32x32x16_bf16 a[64:79], v[120:123], v[128:131], a[64:79]
	s_waitcnt vmcnt(8)
	ds_write_b128 v118, v[68:71] offset:0x5000
	s_waitcnt lgkmcnt(8)
	v_mfma_f32_32x32x16_bf16 a[96:111], v[124:127], v[80:83], a[96:111]
	s_waitcnt vmcnt(7)
	ds_write_b128 v118, v[72:75] offset:0x6000
	v_mfma_f32_32x32x16_bf16 a[112:127], v[124:127], v[112:115], a[112:127]
	v_mfma_f32_32x32x16_bf16 a[128:143], v[124:127], v[128:131], a[128:143]
	s_waitcnt lgkmcnt(0)
	s_barrier
	s_cbranch_scc0 .Lrs0_last
	s_mov_b32 s4, s5
	s_branch .Lrs0_top
.Lrs0_last:
	s_mov_b32 s4, s5
	s_add_i32 s5, s4, 64
	s_min_u32 s6, s5, 0x3e0
	s_lshl_b32 s78, s6, 1
	ds_read_b128 v[44:47], v116 offset:0
	ds_read_b128 v[40:43], v116 offset:0x800
	ds_read_b128 v[36:39], v116 offset:0x1000
	ds_read_b128 v[92:95], v110 offset:0
	v_mfma_f32_32x32x16_bf16 a[144:159], v[136:139], v[80:83], a[144:159]
	ds_read_b128 v[88:91], v110 offset:0x800
	v_mfma_f32_32x32x16_bf16 a[160:175], v[136:139], v[112:115], a[160:175]
	ds_read_b128 v[84:87], v110 offset:0x1000
	v_mfma_f32_32x32x16_bf16 a[176:191], v[136:139], v[128:131], a[176:191]
	ds_read_b128 v[48:51], v110 offset:0x1800
	v_mfma_f32_32x32x16_bf16 a[32:47], v[132:135], v[80:83], a[32:47]
	v_mfma_f32_32x32x16_bf16 a[16:31], v[132:135], v[112:115], a[16:31]
	v_mfma_f32_32x32x16_bf16 a[0:15], v[132:135], v[128:131], a[0:15]
	s_waitcnt lgkmcnt(3)
	v_mfma_f32_32x32x16_bf16 a[80:95], v[92:95], v[44:47], a[80:95]
	ds_read_b128 v[80:83], v117 offset:0
	v_mfma_f32_32x32x16_bf16 a[48:63], v[92:95], v[40:43], a[48:63]
	v_mfma_f32_32x32x16_bf16 a[64:79], v[92:95], v[36:39], a[64:79]
	ds_read_b128 v[112:115], v117 offset:0x800
	s_waitcnt lgkmcnt(4)
	v_mfma_f32_32x32x16_bf16 a[96:111], v[88:91], v[44:47], a[96:111]
	v_mfma_f32_32x32x16_bf16 a[112:127], v[88:91], v[40:43], a[112:127]
	ds_read_b128 v[120:123], v117 offset:0x1000
	v_mfma_f32_32x32x16_bf16 a[128:143], v[88:91], v[36:39], a[128:143]
	ds_read_b128 v[124:127], v111 offset:0
	s_waitcnt lgkmcnt(5)
	v_mfma_f32_32x32x16_bf16 a[144:159], v[84:87], v[44:47], a[144:159]
	ds_read_b128 v[128:131], v111 offset:0x800
	s_min_u32 s4, s4, 0x380
	s_lshl_b32 s78, s4, 1
	v_mfma_f32_32x32x16_bf16 a[160:175], v[84:87], v[40:43], a[160:175]
	ds_read_b128 v[132:135], v111 offset:0x1000
	s_add_i32 s6, s78, 0xc0
	s_mov_b32 s7, s79
	v_mfma_f32_32x32x16_bf16 a[176:191], v[84:87], v[36:39], a[176:191]
	ds_read_b128 v[136:139], v111 offset:0x1800
	s_add_i32 s3, s3, 2
	s_cmp_lt_u32 s3, 30
	s_waitcnt lgkmcnt(7)
	v_mfma_f32_32x32x16_bf16 a[32:47], v[48:51], v[44:47], a[32:47]
	s_waitcnt vmcnt(6)
	ds_write_b128 v118, v[4:7] offset:0x8000
	v_mfma_f32_32x32x16_bf16 a[16:31], v[48:51], v[40:43], a[16:31]
	s_waitcnt vmcnt(5)
	ds_write_b128 v118, v[8:11] offset:0x9000
	v_mfma_f32_32x32x16_bf16 a[0:15], v[48:51], v[36:39], a[0:15]
	s_waitcnt vmcnt(4)
	ds_write_b128 v118, v[12:15] offset:0xa000
	s_waitcnt lgkmcnt(6)
	v_mfma_f32_32x32x16_bf16 a[80:95], v[124:127], v[80:83], a[80:95]
	s_waitcnt vmcnt(3)
	ds_write_b128 v118, v[16:19] offset:0xb000
	v_mfma_f32_32x32x16_bf16 a[48:63], v[124:127], v[112:115], a[48:63]
	s_waitcnt vmcnt(2)
	ds_write_b128 v118, v[20:23] offset:0xc000
	v_mfma_f32_32x32x16_bf16 a[64:79], v[124:127], v[120:123], a[64:79]
	s_waitcnt vmcnt(1)
	ds_write_b128 v118, v[24:27] offset:0xd000
	s_waitcnt lgkmcnt(8)
	v_mfma_f32_32x32x16_bf16 a[96:111], v[128:131], v[80:83], a[96:111]
	s_waitcnt vmcnt(0)
	ds_write_b128 v118, v[28:31] offset:0xe000
	v_mfma_f32_32x32x16_bf16 a[112:127], v[128:131], v[112:115], a[112:127]
	v_mfma_f32_32x32x16_bf16 a[128:143], v[128:131], v[120:123], a[128:143]
	s_waitcnt lgkmcnt(0)
	s_barrier
	ds_read_b128 v[36:39], v116 offset:0x8000
	ds_read_b128 v[40:43], v116 offset:0x8800
	ds_read_b128 v[44:47], v116 offset:0x9000
	ds_read_b128 v[48:51], v110 offset:0x8000
	v_mfma_f32_32x32x16_bf16 a[144:159], v[132:135], v[80:83], a[144:159]
	ds_read_b128 v[84:87], v110 offset:0x8800
	v_mfma_f32_32x32x16_bf16 a[160:175], v[132:135], v[112:115], a[160:175]
	ds_read_b128 v[88:91], v110 offset:0x9000
	v_mfma_f32_32x32x16_bf16 a[176:191], v[132:135], v[120:123], a[176:191]
	ds_read_b128 v[92:95], v110 offset:0x9800
	v_mfma_f32_32x32x16_bf16 a[32:47], v[136:139], v[80:83], a[32:47]
	v_mfma_f32_32x32x16_bf16 a[16:31], v[136:139], v[112:115], a[16:31]
	v_mfma_f32_32x32x16_bf16 a[0:15], v[136:139], v[120:123], a[0:15]
	s_waitcnt lgkmcnt(3)
	v_mfma_f32_32x32x16_bf16 a[80:95], v[48:51], v[36:39], a[80:95]
	ds_read_b128 v[80:83], v117 offset:0x8000
	v_mfma_f32_32x32x16_bf16 a[48:63], v[48:51], v[40:43], a[48:63]
	v_mfma_f32_32x32x16_bf16 a[64:79], v[48:51], v[44:47], a[64:79]
	ds_read_b128 v[112:115], v117 offset:0x8800
	s_waitcnt lgkmcnt(4)
	v_mfma_f32_32x32x16_bf16 a[96:111], v[84:87], v[36:39], a[96:111]
	v_mfma_f32_32x32x16_bf16 a[112:127], v[84:87], v[40:43], a[112:127]
	ds_read_b128 v[128:131], v117 offset:0x9000
	v_mfma_f32_32x32x16_bf16 a[128:143], v[84:87], v[44:47], a[128:143]
	ds_read_b128 v[120:123], v111 offset:0x8000
	s_waitcnt lgkmcnt(5)
	v_mfma_f32_32x32x16_bf16 a[144:159], v[88:91], v[36:39], a[144:159]
	ds_read_b128 v[124:127], v111 offset:0x8800
	v_mfma_f32_32x32x16_bf16 a[160:175], v[88:91], v[40:43], a[160:175]
	ds_read_b128 v[136:139], v111 offset:0x9000
	v_mfma_f32_32x32x16_bf16 a[176:191], v[88:91], v[44:47], a[176:191]
	ds_read_b128 v[132:135], v111 offset:0x9800
	s_waitcnt lgkmcnt(7)
	v_mfma_f32_32x32x16_bf16 a[32:47], v[92:95], v[36:39], a[32:47]
	v_mfma_f32_32x32x16_bf16 a[16:31], v[92:95], v[40:43], a[16:31]
	v_mfma_f32_32x32x16_bf16 a[0:15], v[92:95], v[44:47], a[0:15]
	s_waitcnt lgkmcnt(3)
	v_mfma_f32_32x32x16_bf16 a[80:95], v[120:123], v[80:83], a[80:95]
	v_mfma_f32_32x32x16_bf16 a[48:63], v[120:123], v[112:115], a[48:63]
	v_mfma_f32_32x32x16_bf16 a[64:79], v[120:123], v[128:131], a[64:79]
	s_waitcnt lgkmcnt(2)
	v_mfma_f32_32x32x16_bf16 a[96:111], v[124:127], v[80:83], a[96:111]
	v_mfma_f32_32x32x16_bf16 a[112:127], v[124:127], v[112:115], a[112:127]
	v_mfma_f32_32x32x16_bf16 a[128:143], v[124:127], v[128:131], a[128:143]
	s_waitcnt lgkmcnt(0)
	s_barrier
	v_mfma_f32_32x32x16_bf16 a[144:159], v[136:139], v[80:83], a[144:159]
	v_mfma_f32_32x32x16_bf16 a[160:175], v[136:139], v[112:115], a[160:175]
	v_mfma_f32_32x32x16_bf16 a[176:191], v[136:139], v[128:131], a[176:191]
	s_nop 7
	s_nop 3
	s_branch .LBB0_160

.Lrs3_top:
	s_add_i32 s7, s6, 64
	s_min_u32 s8, s7, 0x3e0
	s_lshl_b32 s78, s8, 1
	ds_read_b128 v[52:55], v116 offset:0
	ds_read_b128 v[48:51], v116 offset:0x800
	ds_read_b128 v[44:47], v116 offset:0x1000
	ds_read_b128 v[96:99], v114 offset:0
	v_mfma_f32_32x32x16_bf16 a[144:159], v[128:131], v[40:43], a[144:159]
	ds_read_b128 v[92:95], v114 offset:0x800
	v_mfma_f32_32x32x16_bf16 a[160:175], v[128:131], v[36:39], a[160:175]
	ds_read_b128 v[88:91], v114 offset:0x1000
	v_add_u32_e32 v142, s78, v140
	v_add_u32_e32 v143, s78, v141
	global_load_dwordx4 v[64:67], v142, s[10:11]
	v_mfma_f32_32x32x16_bf16 a[176:191], v[128:131], v[194:197], a[176:191]
	ds_read_b128 v[56:59], v114 offset:0x1800
	global_load_dwordx4 v[60:63], v142, s[12:13]
	v_mfma_f32_32x32x16_bf16 a[32:47], v[198:201], v[40:43], a[32:47]
	global_load_dwordx4 v[72:75], v142, s[14:15]
	v_mfma_f32_32x32x16_bf16 a[16:31], v[198:201], v[36:39], a[16:31]
	global_load_dwordx4 v[68:71], v142, s[16:17]
	v_mfma_f32_32x32x16_bf16 a[0:15], v[198:201], v[194:197], a[0:15]
	global_load_dwordx4 v[84:87], v143, s[18:19]
	s_waitcnt lgkmcnt(3)
	v_mfma_f32_32x32x16_bf16 a[48:63], v[96:99], v[52:55], a[48:63]
	ds_read_b128 v[36:39], v117 offset:0
	v_mfma_f32_32x32x16_bf16 a[64:79], v[96:99], v[48:51], a[64:79]
	global_load_dwordx4 v[76:79], v143, s[20:21]
	v_mfma_f32_32x32x16_bf16 a[80:95], v[96:99], v[44:47], a[80:95]
	ds_read_b128 v[40:43], v117 offset:0x800
	s_waitcnt lgkmcnt(4)
	v_mfma_f32_32x32x16_bf16 a[96:111], v[92:95], v[52:55], a[96:111]
	global_load_dwordx4 v[80:83], v143, s[22:23]
	v_mfma_f32_32x32x16_bf16 a[112:127], v[92:95], v[48:51], a[112:127]
	ds_read_b128 v[120:123], v117 offset:0x1000
	v_mfma_f32_32x32x16_bf16 a[128:143], v[92:95], v[44:47], a[128:143]
	ds_read_b128 v[124:127], v115 offset:0
	s_waitcnt lgkmcnt(5)
	v_mfma_f32_32x32x16_bf16 a[144:159], v[88:91], v[52:55], a[144:159]
	ds_read_b128 v[128:131], v115 offset:0x800
	s_min_u32 s6, s6, 0x380
	s_lshl_b32 s78, s6, 1
	v_mfma_f32_32x32x16_bf16 a[160:175], v[88:91], v[48:51], a[160:175]
	ds_read_b128 v[132:135], v115 offset:0x1000
	s_add_i32 s8, s78, 0xc0
	s_mov_b32 s9, s79
	v_mfma_f32_32x32x16_bf16 a[176:191], v[88:91], v[44:47], a[176:191]
	ds_read_b128 v[136:139], v115 offset:0x1800
	s_add_i32 s5, s5, 2
	s_cmp_lt_u32 s5, 28
	s_waitcnt lgkmcnt(7)
	v_mfma_f32_32x32x16_bf16 a[32:47], v[56:59], v[52:55], a[32:47]
	s_waitcnt vmcnt(13)
	ds_write_b128 v118, v[4:7] offset:0x8000
	v_mfma_f32_32x32x16_bf16 a[16:31], v[56:59], v[48:51], a[16:31]
	s_waitcnt vmcnt(12)
	ds_write_b128 v118, v[8:11] offset:0x9000
	v_mfma_f32_32x32x16_bf16 a[0:15], v[56:59], v[44:47], a[0:15]
	s_waitcnt vmcnt(11)
	ds_write_b128 v118, v[12:15] offset:0xa000
	s_waitcnt lgkmcnt(6)
	v_mfma_f32_32x32x16_bf16 a[48:63], v[124:127], v[36:39], a[48:63]
	s_waitcnt vmcnt(10)
	ds_write_b128 v118, v[16:19] offset:0xb000
	v_mfma_f32_32x32x16_bf16 a[64:79], v[124:127], v[40:43], a[64:79]
	s_waitcnt vmcnt(9)
	ds_write_b128 v118, v[20:23] offset:0xc000
	v_mfma_f32_32x32x16_bf16 a[80:95], v[124:127], v[120:123], a[80:95]
	s_waitcnt vmcnt(8)
	ds_write_b128 v118, v[24:27] offset:0xd000
	s_waitcnt lgkmcnt(8)
	v_mfma_f32_32x32x16_bf16 a[96:111], v[128:131], v[36:39], a[96:111]
	s_waitcnt vmcnt(7)
	ds_write_b128 v118, v[28:31] offset:0xe000
	v_mfma_f32_32x32x16_bf16 a[112:127], v[128:131], v[40:43], a[112:127]
	v_mfma_f32_32x32x16_bf16 a[128:143], v[128:131], v[120:123], a[128:143]
	s_waitcnt lgkmcnt(0)
	s_barrier
	ds_read_b128 v[44:47], v116 offset:0x8000
	ds_read_b128 v[48:51], v116 offset:0x8800
	ds_read_b128 v[52:55], v116 offset:0x9000
	ds_read_b128 v[56:59], v114 offset:0x8000
	v_mfma_f32_32x32x16_bf16 a[144:159], v[132:135], v[36:39], a[144:159]
	ds_read_b128 v[88:91], v114 offset:0x8800
	v_mfma_f32_32x32x16_bf16 a[160:175], v[132:135], v[40:43], a[160:175]
	ds_read_b128 v[92:95], v114 offset:0x9000
	v_add_u32_e32 v142, s8, v140
	v_add_u32_e32 v143, s8, v141
	global_load_dwordx4 v[4:7], v142, s[10:11]
	v_mfma_f32_32x32x16_bf16 a[176:191], v[132:135], v[120:123], a[176:191]
	ds_read_b128 v[96:99], v114 offset:0x9800
	global_load_dwordx4 v[8:11], v142, s[12:13]
	v_mfma_f32_32x32x16_bf16 a[32:47], v[136:139], v[36:39], a[32:47]
	global_load_dwordx4 v[12:15], v142, s[14:15]
	v_mfma_f32_32x32x16_bf16 a[16:31], v[136:139], v[40:43], a[16:31]
	global_load_dwordx4 v[16:19], v142, s[16:17]
	v_mfma_f32_32x32x16_bf16 a[0:15], v[136:139], v[120:123], a[0:15]
	global_load_dwordx4 v[20:23], v143, s[18:19]
	s_waitcnt lgkmcnt(3)
	v_mfma_f32_32x32x16_bf16 a[48:63], v[56:59], v[44:47], a[48:63]
	ds_read_b128 v[40:43], v117 offset:0x8000
	v_mfma_f32_32x32x16_bf16 a[64:79], v[56:59], v[48:51], a[64:79]
	global_load_dwordx4 v[24:27], v143, s[20:21]
	v_mfma_f32_32x32x16_bf16 a[80:95], v[56:59], v[52:55], a[80:95]
	ds_read_b128 v[36:39], v117 offset:0x8800
	s_waitcnt lgkmcnt(4)
	v_mfma_f32_32x32x16_bf16 a[96:111], v[88:91], v[44:47], a[96:111]
	global_load_dwordx4 v[28:31], v143, s[22:23]
	v_mfma_f32_32x32x16_bf16 a[112:127], v[88:91], v[48:51], a[112:127]
	ds_read_b128 v[194:197], v117 offset:0x9000
	v_mfma_f32_32x32x16_bf16 a[128:143], v[88:91], v[52:55], a[128:143]
	ds_read_b128 v[120:123], v115 offset:0x8000
	s_waitcnt lgkmcnt(5)
	v_mfma_f32_32x32x16_bf16 a[144:159], v[92:95], v[44:47], a[144:159]
	ds_read_b128 v[124:127], v115 offset:0x8800
	v_mfma_f32_32x32x16_bf16 a[160:175], v[92:95], v[48:51], a[160:175]
	ds_read_b128 v[128:131], v115 offset:0x9000
	v_mfma_f32_32x32x16_bf16 a[176:191], v[92:95], v[52:55], a[176:191]
	ds_read_b128 v[198:201], v115 offset:0x9800
	s_waitcnt lgkmcnt(7)
	v_mfma_f32_32x32x16_bf16 a[32:47], v[96:99], v[44:47], a[32:47]
	s_waitcnt vmcnt(13)
	ds_write_b128 v118, v[64:67] offset:0
	v_mfma_f32_32x32x16_bf16 a[16:31], v[96:99], v[48:51], a[16:31]
	s_waitcnt vmcnt(12)
	ds_write_b128 v118, v[60:63] offset:0x1000
	v_mfma_f32_32x32x16_bf16 a[0:15], v[96:99], v[52:55], a[0:15]
	s_waitcnt vmcnt(11)
	ds_write_b128 v118, v[72:75] offset:0x2000
	s_waitcnt lgkmcnt(6)
	v_mfma_f32_32x32x16_bf16 a[48:63], v[120:123], v[40:43], a[48:63]
	s_waitcnt vmcnt(10)
	ds_write_b128 v118, v[68:71] offset:0x3000
	v_mfma_f32_32x32x16_bf16 a[64:79], v[120:123], v[36:39], a[64:79]
	s_waitcnt vmcnt(9)
	ds_write_b128 v118, v[84:87] offset:0x4000
	v_mfma_f32_32x32x16_bf16 a[80:95], v[120:123], v[194:197], a[80:95]
	s_waitcnt vmcnt(8)
	ds_write_b128 v118, v[76:79] offset:0x5000
	s_waitcnt lgkmcnt(8)
	v_mfma_f32_32x32x16_bf16 a[96:111], v[124:127], v[40:43], a[96:111]
	s_waitcnt vmcnt(7)
	ds_write_b128 v118, v[80:83] offset:0x6000
	v_mfma_f32_32x32x16_bf16 a[112:127], v[124:127], v[36:39], a[112:127]
	v_mfma_f32_32x32x16_bf16 a[128:143], v[124:127], v[194:197], a[128:143]
	s_waitcnt lgkmcnt(0)
	s_barrier
	s_cbranch_scc0 .Lrs3_last
	s_mov_b32 s6, s7
	s_branch .Lrs3_top
.Lrs3_last:
	s_mov_b32 s6, s7
	s_add_i32 s7, s6, 64
	s_min_u32 s8, s7, 0x3e0
	s_lshl_b32 s78, s8, 1
	ds_read_b128 v[52:55], v116 offset:0
	ds_read_b128 v[48:51], v116 offset:0x800
	ds_read_b128 v[44:47], v116 offset:0x1000
	ds_read_b128 v[96:99], v114 offset:0
	v_mfma_f32_32x32x16_bf16 a[144:159], v[128:131], v[40:43], a[144:159]
	ds_read_b128 v[92:95], v114 offset:0x800
	v_mfma_f32_32x32x16_bf16 a[160:175], v[128:131], v[36:39], a[160:175]
	ds_read_b128 v[88:91], v114 offset:0x1000
	v_mfma_f32_32x32x16_bf16 a[176:191], v[128:131], v[194:197], a[176:191]
	ds_read_b128 v[56:59], v114 offset:0x1800
	v_mfma_f32_32x32x16_bf16 a[32:47], v[198:201], v[40:43], a[32:47]
	v_mfma_f32_32x32x16_bf16 a[16:31], v[198:201], v[36:39], a[16:31]
	v_mfma_f32_32x32x16_bf16 a[0:15], v[198:201], v[194:197], a[0:15]
	s_waitcnt lgkmcnt(3)
	v_mfma_f32_32x32x16_bf16 a[48:63], v[96:99], v[52:55], a[48:63]
	ds_read_b128 v[36:39], v117 offset:0
	v_mfma_f32_32x32x16_bf16 a[64:79], v[96:99], v[48:51], a[64:79]
	v_mfma_f32_32x32x16_bf16 a[80:95], v[96:99], v[44:47], a[80:95]
	ds_read_b128 v[40:43], v117 offset:0x800
	s_waitcnt lgkmcnt(4)
	v_mfma_f32_32x32x16_bf16 a[96:111], v[92:95], v[52:55], a[96:111]
	v_mfma_f32_32x32x16_bf16 a[112:127], v[92:95], v[48:51], a[112:127]
	ds_read_b128 v[120:123], v117 offset:0x1000
	v_mfma_f32_32x32x16_bf16 a[128:143], v[92:95], v[44:47], a[128:143]
	ds_read_b128 v[124:127], v115 offset:0
	s_waitcnt lgkmcnt(5)
	v_mfma_f32_32x32x16_bf16 a[144:159], v[88:91], v[52:55], a[144:159]
	ds_read_b128 v[128:131], v115 offset:0x800
	s_min_u32 s6, s6, 0x380
	s_lshl_b32 s78, s6, 1
	v_mfma_f32_32x32x16_bf16 a[160:175], v[88:91], v[48:51], a[160:175]
	ds_read_b128 v[132:135], v115 offset:0x1000
	s_add_i32 s8, s78, 0xc0
	s_mov_b32 s9, s79
	v_mfma_f32_32x32x16_bf16 a[176:191], v[88:91], v[44:47], a[176:191]
	ds_read_b128 v[136:139], v115 offset:0x1800
	s_add_i32 s5, s5, 2
	s_cmp_lt_u32 s5, 30
	s_waitcnt lgkmcnt(7)
	v_mfma_f32_32x32x16_bf16 a[32:47], v[56:59], v[52:55], a[32:47]
	s_waitcnt vmcnt(6)
	ds_write_b128 v118, v[4:7] offset:0x8000
	v_mfma_f32_32x32x16_bf16 a[16:31], v[56:59], v[48:51], a[16:31]
	s_waitcnt vmcnt(5)
	ds_write_b128 v118, v[8:11] offset:0x9000
	v_mfma_f32_32x32x16_bf16 a[0:15], v[56:59], v[44:47], a[0:15]
	s_waitcnt vmcnt(4)
	ds_write_b128 v118, v[12:15] offset:0xa000
	s_waitcnt lgkmcnt(6)
	v_mfma_f32_32x32x16_bf16 a[48:63], v[124:127], v[36:39], a[48:63]
	s_waitcnt vmcnt(3)
	ds_write_b128 v118, v[16:19] offset:0xb000
	v_mfma_f32_32x32x16_bf16 a[64:79], v[124:127], v[40:43], a[64:79]
	s_waitcnt vmcnt(2)
	ds_write_b128 v118, v[20:23] offset:0xc000
	v_mfma_f32_32x32x16_bf16 a[80:95], v[124:127], v[120:123], a[80:95]
	s_waitcnt vmcnt(1)
	ds_write_b128 v118, v[24:27] offset:0xd000
	s_waitcnt lgkmcnt(8)
	v_mfma_f32_32x32x16_bf16 a[96:111], v[128:131], v[36:39], a[96:111]
	s_waitcnt vmcnt(0)
	ds_write_b128 v118, v[28:31] offset:0xe000
	v_mfma_f32_32x32x16_bf16 a[112:127], v[128:131], v[40:43], a[112:127]
	v_mfma_f32_32x32x16_bf16 a[128:143], v[128:131], v[120:123], a[128:143]
	s_waitcnt lgkmcnt(0)
	s_barrier
	ds_read_b128 v[44:47], v116 offset:0x8000
	ds_read_b128 v[48:51], v116 offset:0x8800
	ds_read_b128 v[52:55], v116 offset:0x9000
	ds_read_b128 v[56:59], v114 offset:0x8000
	v_mfma_f32_32x32x16_bf16 a[144:159], v[132:135], v[36:39], a[144:159]
	ds_read_b128 v[88:91], v114 offset:0x8800
	v_mfma_f32_32x32x16_bf16 a[160:175], v[132:135], v[40:43], a[160:175]
	ds_read_b128 v[92:95], v114 offset:0x9000
	v_mfma_f32_32x32x16_bf16 a[176:191], v[132:135], v[120:123], a[176:191]
	ds_read_b128 v[96:99], v114 offset:0x9800
	v_mfma_f32_32x32x16_bf16 a[32:47], v[136:139], v[36:39], a[32:47]
	v_mfma_f32_32x32x16_bf16 a[16:31], v[136:139], v[40:43], a[16:31]
	v_mfma_f32_32x32x16_bf16 a[0:15], v[136:139], v[120:123], a[0:15]
	s_waitcnt lgkmcnt(3)
	v_mfma_f32_32x32x16_bf16 a[48:63], v[56:59], v[44:47], a[48:63]
	ds_read_b128 v[40:43], v117 offset:0x8000
	v_mfma_f32_32x32x16_bf16 a[64:79], v[56:59], v[48:51], a[64:79]
	v_mfma_f32_32x32x16_bf16 a[80:95], v[56:59], v[52:55], a[80:95]
	ds_read_b128 v[36:39], v117 offset:0x8800
	s_waitcnt lgkmcnt(4)
	v_mfma_f32_32x32x16_bf16 a[96:111], v[88:91], v[44:47], a[96:111]
	v_mfma_f32_32x32x16_bf16 a[112:127], v[88:91], v[48:51], a[112:127]
	ds_read_b128 v[194:197], v117 offset:0x9000
	v_mfma_f32_32x32x16_bf16 a[128:143], v[88:91], v[52:55], a[128:143]
	ds_read_b128 v[120:123], v115 offset:0x8000
	s_waitcnt lgkmcnt(5)
	v_mfma_f32_32x32x16_bf16 a[144:159], v[92:95], v[44:47], a[144:159]
	ds_read_b128 v[124:127], v115 offset:0x8800
	v_mfma_f32_32x32x16_bf16 a[160:175], v[92:95], v[48:51], a[160:175]
	ds_read_b128 v[128:131], v115 offset:0x9000
	v_mfma_f32_32x32x16_bf16 a[176:191], v[92:95], v[52:55], a[176:191]
	ds_read_b128 v[198:201], v115 offset:0x9800
	s_waitcnt lgkmcnt(7)
	v_mfma_f32_32x32x16_bf16 a[32:47], v[96:99], v[44:47], a[32:47]
	v_mfma_f32_32x32x16_bf16 a[16:31], v[96:99], v[48:51], a[16:31]
	v_mfma_f32_32x32x16_bf16 a[0:15], v[96:99], v[52:55], a[0:15]
	s_waitcnt lgkmcnt(3)
	v_mfma_f32_32x32x16_bf16 a[48:63], v[120:123], v[40:43], a[48:63]
	v_mfma_f32_32x32x16_bf16 a[64:79], v[120:123], v[36:39], a[64:79]
	v_mfma_f32_32x32x16_bf16 a[80:95], v[120:123], v[194:197], a[80:95]
	s_waitcnt lgkmcnt(2)
	v_mfma_f32_32x32x16_bf16 a[96:111], v[124:127], v[40:43], a[96:111]
	v_mfma_f32_32x32x16_bf16 a[112:127], v[124:127], v[36:39], a[112:127]
	v_mfma_f32_32x32x16_bf16 a[128:143], v[124:127], v[194:197], a[128:143]
	s_waitcnt lgkmcnt(0)
	s_barrier
	v_mfma_f32_32x32x16_bf16 a[144:159], v[128:131], v[40:43], a[144:159]
	v_mfma_f32_32x32x16_bf16 a[160:175], v[128:131], v[36:39], a[160:175]
	v_mfma_f32_32x32x16_bf16 a[176:191], v[128:131], v[194:197], a[176:191]
	s_nop 7
	s_nop 3
	s_branch .LBB0_203

.Lrs4_top:
	s_add_i32 s5, s4, 64
	s_min_u32 s6, s5, 0x3e0
	s_lshl_b32 s78, s6, 1
	ds_read_b128 v[48:51], v82 offset:0
	ds_read_b128 v[44:47], v82 offset:0x800
	ds_read_b128 v[64:67], v80 offset:0
	v_mfma_f32_32x32x16_bf16 a[96:111], v[94:97], v[40:43], a[96:111]
	ds_read_b128 v[60:63], v80 offset:0x800
	v_mfma_f32_32x32x16_bf16 a[112:127], v[94:97], v[128:131], a[112:127]
	ds_read_b128 v[56:59], v80 offset:0x1000
	v_add_u32_e32 v146, s78, v144
	v_add_u32_e32 v147, s78, v145
	global_load_dwordx4 v[106:109], v146, s[8:9]
	v_mfma_f32_32x32x16_bf16 a[16:31], v[132:135], v[40:43], a[16:31]
	ds_read_b128 v[52:55], v80 offset:0x1800
	global_load_dwordx4 v[110:113], v146, s[10:11]
	v_mfma_f32_32x32x16_bf16 a[0:15], v[132:135], v[128:131], a[0:15]
	global_load_dwordx4 v[114:117], v146, s[12:13]
	s_waitcnt lgkmcnt(3)
	v_mfma_f32_32x32x16_bf16 a[32:47], v[64:67], v[48:51], a[32:47]
	ds_read_b128 v[40:43], v83 offset:0
	v_mfma_f32_32x32x16_bf16 a[48:63], v[64:67], v[44:47], a[48:63]
	global_load_dwordx4 v[118:121], v146, s[14:15]
	s_waitcnt lgkmcnt(3)
	v_mfma_f32_32x32x16_bf16 a[64:79], v[60:63], v[48:51], a[64:79]
	ds_read_b128 v[86:89], v83 offset:0x800
	v_mfma_f32_32x32x16_bf16 a[80:95], v[60:63], v[44:47], a[80:95]
	global_load_dwordx4 v[122:125], v147, s[16:17]
	s_waitcnt lgkmcnt(3)
	v_mfma_f32_32x32x16_bf16 a[96:111], v[56:59], v[48:51], a[96:111]
	ds_read_b128 v[90:93], v81 offset:0
	v_mfma_f32_32x32x16_bf16 a[112:127], v[56:59], v[44:47], a[112:127]
	global_load_dwordx4 v[140:143], v147, s[18:19]
	s_waitcnt vmcnt(11)
	ds_write_b128 v84, v[4:7] offset:0x8000
	s_waitcnt lgkmcnt(4)
	v_mfma_f32_32x32x16_bf16 a[16:31], v[52:55], v[48:51], a[16:31]
	ds_read_b128 v[94:97], v81 offset:0x800
	s_min_u32 s4, s4, 0x380
	s_lshl_b32 s78, s4, 1
	s_waitcnt vmcnt(10)
	ds_write_b128 v84, v[8:11] offset:0x9000
	v_mfma_f32_32x32x16_bf16 a[0:15], v[52:55], v[44:47], a[0:15]
	ds_read_b128 v[98:101], v81 offset:0x1000
	s_add_i32 s6, s78, 0xc0
	s_mov_b32 s7, s79
	s_waitcnt vmcnt(9)
	ds_write_b128 v84, v[12:15] offset:0xa000
	s_waitcnt lgkmcnt(5)
	v_mfma_f32_32x32x16_bf16 a[32:47], v[90:93], v[40:43], a[32:47]
	ds_read_b128 v[102:105], v81 offset:0x1800
	s_add_i32 s3, s3, 2
	s_cmp_lt_u32 s3, 28
	s_waitcnt vmcnt(8)
	ds_write_b128 v84, v[16:19] offset:0xb000
	v_mfma_f32_32x32x16_bf16 a[48:63], v[90:93], v[86:89], a[48:63]
	s_waitcnt vmcnt(7)
	ds_write_b128 v84, v[20:23] offset:0xc000
	s_waitcnt lgkmcnt(6)
	v_mfma_f32_32x32x16_bf16 a[64:79], v[94:97], v[40:43], a[64:79]
	s_waitcnt vmcnt(6)
	ds_write_b128 v84, v[24:27] offset:0xd000
	v_mfma_f32_32x32x16_bf16 a[80:95], v[94:97], v[86:89], a[80:95]
	s_waitcnt lgkmcnt(0)
	s_barrier
	ds_read_b128 v[44:47], v82 offset:0x8000
	ds_read_b128 v[48:51], v82 offset:0x8800
	ds_read_b128 v[52:55], v80 offset:0x8000
	v_mfma_f32_32x32x16_bf16 a[96:111], v[98:101], v[40:43], a[96:111]
	ds_read_b128 v[56:59], v80 offset:0x8800
	v_mfma_f32_32x32x16_bf16 a[112:127], v[98:101], v[86:89], a[112:127]
	ds_read_b128 v[60:63], v80 offset:0x9000
	v_add_u32_e32 v146, s6, v144
	v_add_u32_e32 v147, s6, v145
	global_load_dwordx4 v[4:7], v146, s[8:9]
	v_mfma_f32_32x32x16_bf16 a[16:31], v[102:105], v[40:43], a[16:31]
	ds_read_b128 v[64:67], v80 offset:0x9800
	global_load_dwordx4 v[8:11], v146, s[10:11]
	v_mfma_f32_32x32x16_bf16 a[0:15], v[102:105], v[86:89], a[0:15]
	global_load_dwordx4 v[12:15], v146, s[12:13]
	s_waitcnt lgkmcnt(3)
	v_mfma_f32_32x32x16_bf16 a[32:47], v[52:55], v[44:47], a[32:47]
	ds_read_b128 v[40:43], v83 offset:0x8000
	v_mfma_f32_32x32x16_bf16 a[48:63], v[52:55], v[48:51], a[48:63]
	global_load_dwordx4 v[16:19], v146, s[14:15]
	s_waitcnt lgkmcnt(3)
	v_mfma_f32_32x32x16_bf16 a[64:79], v[56:59], v[44:47], a[64:79]
	ds_read_b128 v[128:131], v83 offset:0x8800
	v_mfma_f32_32x32x16_bf16 a[80:95], v[56:59], v[48:51], a[80:95]
	global_load_dwordx4 v[20:23], v147, s[16:17]
	s_waitcnt lgkmcnt(3)
	v_mfma_f32_32x32x16_bf16 a[96:111], v[60:63], v[44:47], a[96:111]
	ds_read_b128 v[86:89], v81 offset:0x8000
	v_mfma_f32_32x32x16_bf16 a[112:127], v[60:63], v[48:51], a[112:127]
	global_load_dwordx4 v[24:27], v147, s[18:19]
	s_waitcnt vmcnt(11)
	ds_write_b128 v84, v[106:109] offset:0
	s_waitcnt lgkmcnt(4)
	v_mfma_f32_32x32x16_bf16 a[16:31], v[64:67], v[44:47], a[16:31]
	ds_read_b128 v[90:93], v81 offset:0x8800
	s_waitcnt vmcnt(10)
	ds_write_b128 v84, v[110:113] offset:0x1000
	v_mfma_f32_32x32x16_bf16 a[0:15], v[64:67], v[48:51], a[0:15]
	ds_read_b128 v[94:97], v81 offset:0x9000
	s_waitcnt vmcnt(9)
	ds_write_b128 v84, v[114:117] offset:0x2000
	s_waitcnt lgkmcnt(5)
	v_mfma_f32_32x32x16_bf16 a[32:47], v[86:89], v[40:43], a[32:47]
	ds_read_b128 v[132:135], v81 offset:0x9800
	s_waitcnt vmcnt(8)
	ds_write_b128 v84, v[118:121] offset:0x3000
	v_mfma_f32_32x32x16_bf16 a[48:63], v[86:89], v[128:131], a[48:63]
	s_waitcnt vmcnt(7)
	ds_write_b128 v84, v[122:125] offset:0x4000
	s_waitcnt lgkmcnt(6)
	v_mfma_f32_32x32x16_bf16 a[64:79], v[90:93], v[40:43], a[64:79]
	s_waitcnt vmcnt(6)
	ds_write_b128 v84, v[140:143] offset:0x5000
	v_mfma_f32_32x32x16_bf16 a[80:95], v[90:93], v[128:131], a[80:95]
	s_waitcnt lgkmcnt(0)
	s_barrier
	s_cbranch_scc0 .Lrs4_last
	s_mov_b32 s4, s5
	s_branch .Lrs4_top

.LBB0_773:
	v_mov_b32_e32 v90, 0
	v_mov_b32_e32 v91, 0
	v_mov_b32_e32 v92, 0
	v_mov_b32_e32 v93, 0
	v_mov_b32_e32 v194, 0
	v_mov_b32_e32 v195, 0
	v_mov_b32_e32 v196, 0
	v_mov_b32_e32 v197, 0
	v_mov_b32_e32 v198, 0
	v_mov_b32_e32 v199, 0
	v_mov_b32_e32 v200, 0
	v_mov_b32_e32 v201, 0
	v_mov_b32_e32 v202, 0
	v_mov_b32_e32 v203, 0
	v_mov_b32_e32 v204, 0
	v_mov_b32_e32 v205, 0
	s_nop 1
	v_readfirstlane_b32 s8, v64
	v_readfirstlane_b32 s9, v65
	v_readfirstlane_b32 s10, v68
	v_readfirstlane_b32 s11, v69
	v_readfirstlane_b32 s12, v70
	v_readfirstlane_b32 s13, v71
	v_readfirstlane_b32 s14, v72
	v_readfirstlane_b32 s15, v73
	v_readfirstlane_b32 s16, v66
	v_readfirstlane_b32 s17, v67
	v_readfirstlane_b32 s18, v74
	v_readfirstlane_b32 s19, v75
	v_subrev_u32_e32 v140, s8, v64
	v_subrev_u32_e32 v141, s16, v66
	s_nop 4
.Lrs5_top:
	s_add_i32 s4, s3, 64
	s_min_u32 s5, s4, 0x3e0
	s_lshl_b32 s78, s5, 1
	ds_read_b128 v[44:47], v78 offset:0
	ds_read_b128 v[40:43], v78 offset:0x800
	ds_read_b128 v[60:63], v76 offset:0
	v_mfma_f32_32x32x16_bf16 a[48:63], v[90:93], v[202:205], a[48:63]
	ds_read_b128 v[56:59], v76 offset:0x800
	v_mfma_f32_32x32x16_bf16 a[16:31], v[90:93], v[194:197], a[16:31]
	ds_read_b128 v[52:55], v76 offset:0x1000
	v_add_u32_e32 v142, s78, v140
	v_add_u32_e32 v143, s78, v141
	global_load_dwordx4 v[106:109], v142, s[8:9]
	v_mfma_f32_32x32x16_bf16 a[0:15], v[198:201], v[202:205], a[0:15]
	ds_read_b128 v[48:51], v76 offset:0x1800
	global_load_dwordx4 v[110:113], v142, s[10:11]
	v_mfma_f32_32x32x16_bf16 a[128:143], v[198:201], v[194:197], a[128:143]
	global_load_dwordx4 v[114:117], v142, s[12:13]
	s_waitcnt lgkmcnt(3)
	v_mfma_f32_32x32x16_bf16 a[112:127], v[60:63], v[44:47], a[112:127]
	ds_read_b128 v[82:85], v79 offset:0
	v_mfma_f32_32x32x16_bf16 a[96:111], v[60:63], v[40:43], a[96:111]
	global_load_dwordx4 v[118:121], v142, s[14:15]
	s_waitcnt lgkmcnt(3)
	v_mfma_f32_32x32x16_bf16 a[80:95], v[56:59], v[44:47], a[80:95]
	ds_read_b128 v[86:89], v79 offset:0x800
	v_mfma_f32_32x32x16_bf16 a[64:79], v[56:59], v[40:43], a[64:79]
	global_load_dwordx4 v[122:125], v143, s[16:17]
	s_waitcnt lgkmcnt(3)
	v_mfma_f32_32x32x16_bf16 a[48:63], v[52:55], v[44:47], a[48:63]
	ds_read_b128 v[90:93], v77 offset:0
	v_mfma_f32_32x32x16_bf16 a[16:31], v[52:55], v[40:43], a[16:31]
	global_load_dwordx4 v[126:129], v143, s[18:19]
	s_waitcnt vmcnt(11)
	ds_write_b128 v80, v[4:7] offset:0x8000
	s_waitcnt lgkmcnt(4)
	v_mfma_f32_32x32x16_bf16 a[0:15], v[48:51], v[44:47], a[0:15]
	ds_read_b128 v[94:97], v77 offset:0x800
	s_min_u32 s3, s3, 0x380
	s_lshl_b32 s78, s3, 1
	s_waitcnt vmcnt(10)
	ds_write_b128 v80, v[8:11] offset:0x9000
	v_mfma_f32_32x32x16_bf16 a[128:143], v[48:51], v[40:43], a[128:143]
	ds_read_b128 v[98:101], v77 offset:0x1000
	s_add_i32 s6, s78, 0xc0
	s_mov_b32 s7, s79
	s_waitcnt vmcnt(9)
	ds_write_b128 v80, v[12:15] offset:0xa000
	s_waitcnt lgkmcnt(5)
	v_mfma_f32_32x32x16_bf16 a[112:127], v[90:93], v[82:85], a[112:127]
	ds_read_b128 v[102:105], v77 offset:0x1800
	s_add_i32 s2, s2, 2
	s_cmp_gt_u32 s2, 27
	s_waitcnt vmcnt(8)
	ds_write_b128 v80, v[16:19] offset:0xb000
	v_mfma_f32_32x32x16_bf16 a[96:111], v[90:93], v[86:89], a[96:111]
	s_waitcnt vmcnt(7)
	ds_write_b128 v80, v[20:23] offset:0xc000
	s_waitcnt lgkmcnt(6)
	v_mfma_f32_32x32x16_bf16 a[80:95], v[94:97], v[82:85], a[80:95]
	s_waitcnt vmcnt(6)
	ds_write_b128 v80, v[24:27] offset:0xd000
	v_mfma_f32_32x32x16_bf16 a[64:79], v[94:97], v[86:89], a[64:79]
	s_waitcnt lgkmcnt(0)
	s_barrier
	ds_read_b128 v[40:43], v78 offset:0x8000
	ds_read_b128 v[44:47], v78 offset:0x8800
	ds_read_b128 v[48:51], v76 offset:0x8000
	v_mfma_f32_32x32x16_bf16 a[48:63], v[98:101], v[82:85], a[48:63]
	ds_read_b128 v[52:55], v76 offset:0x8800
	v_mfma_f32_32x32x16_bf16 a[16:31], v[98:101], v[86:89], a[16:31]
	ds_read_b128 v[56:59], v76 offset:0x9000
	v_add_u32_e32 v142, s6, v140
	v_add_u32_e32 v143, s6, v141
	global_load_dwordx4 v[4:7], v142, s[8:9]
	v_mfma_f32_32x32x16_bf16 a[0:15], v[102:105], v[82:85], a[0:15]
	ds_read_b128 v[60:63], v76 offset:0x9800
	global_load_dwordx4 v[8:11], v142, s[10:11]
	v_mfma_f32_32x32x16_bf16 a[128:143], v[102:105], v[86:89], a[128:143]
	global_load_dwordx4 v[12:15], v142, s[12:13]
	s_waitcnt lgkmcnt(3)
	v_mfma_f32_32x32x16_bf16 a[112:127], v[48:51], v[40:43], a[112:127]
	ds_read_b128 v[202:205], v79 offset:0x8000
	v_mfma_f32_32x32x16_bf16 a[96:111], v[48:51], v[44:47], a[96:111]
	global_load_dwordx4 v[16:19], v142, s[14:15]
	s_waitcnt lgkmcnt(3)
	v_mfma_f32_32x32x16_bf16 a[80:95], v[52:55], v[40:43], a[80:95]
	ds_read_b128 v[194:197], v79 offset:0x8800
	v_mfma_f32_32x32x16_bf16 a[64:79], v[52:55], v[44:47], a[64:79]
	global_load_dwordx4 v[20:23], v143, s[16:17]
	s_waitcnt lgkmcnt(3)
	v_mfma_f32_32x32x16_bf16 a[48:63], v[56:59], v[40:43], a[48:63]
	ds_read_b128 v[82:85], v77 offset:0x8000
	v_mfma_f32_32x32x16_bf16 a[16:31], v[56:59], v[44:47], a[16:31]
	global_load_dwordx4 v[24:27], v143, s[18:19]
	s_waitcnt vmcnt(11)
	ds_write_b128 v80, v[106:109] offset:0
	s_waitcnt lgkmcnt(4)
	v_mfma_f32_32x32x16_bf16 a[0:15], v[60:63], v[40:43], a[0:15]
	ds_read_b128 v[86:89], v77 offset:0x8800
	s_waitcnt vmcnt(10)
	ds_write_b128 v80, v[110:113] offset:0x1000
	v_mfma_f32_32x32x16_bf16 a[128:143], v[60:63], v[44:47], a[128:143]
	ds_read_b128 v[90:93], v77 offset:0x9000
	s_waitcnt vmcnt(9)
	ds_write_b128 v80, v[114:117] offset:0x2000
	s_waitcnt lgkmcnt(5)
	v_mfma_f32_32x32x16_bf16 a[112:127], v[82:85], v[202:205], a[112:127]
	ds_read_b128 v[198:201], v77 offset:0x9800
	s_waitcnt vmcnt(8)
	ds_write_b128 v80, v[118:121] offset:0x3000
	v_mfma_f32_32x32x16_bf16 a[96:111], v[82:85], v[194:197], a[96:111]
	s_waitcnt vmcnt(7)
	ds_write_b128 v80, v[122:125] offset:0x4000
	s_waitcnt lgkmcnt(6)
	v_mfma_f32_32x32x16_bf16 a[80:95], v[86:89], v[202:205], a[80:95]
	s_waitcnt vmcnt(6)
	ds_write_b128 v80, v[126:129] offset:0x5000
	v_mfma_f32_32x32x16_bf16 a[64:79], v[86:89], v[194:197], a[64:79]
	s_waitcnt lgkmcnt(0)
	s_barrier
	s_cbranch_scc1 .Lrs5_last
	s_mov_b32 s3, s4
	s_branch .Lrs5_top
